# new grid barrier (one level fewer), attention: window masks only on edge tiles, batched K-fragment LDS reads, prologue loads together
# speedup vs baseline: 1.0861x; 1.0108x over previous
.LBB0_18:
	s_add_u32 s2, s50, 0xc8
	s_addc_u32 s3, s51, 0
	v_writelane_b32 v254, s2, 2
	s_lshr_b32 s65, s10, 8
	s_bfe_u32 s49, s10, 0x20006
	v_writelane_b32 v254, s3, 3
	s_mul_i32 s2, s65, 0x13c00
	s_add_i32 s33, s2, 0
	s_lshl_b32 s2, s49, 5
	v_writelane_b32 v254, s2, 4
	s_add_i32 s2, s33, 0x12000
	v_writelane_b32 v254, s2, 5
	s_add_i32 s2, s33, 0x13400
	s_and_b32 s48, s10, 0xffffffc0
	s_add_i32 s73, s33, 0x11c00
	s_add_i32 s60, s33, 0x12400
	s_add_i32 s64, s33, 0x12800
	s_add_i32 s72, s33, 0x12c00
	v_writelane_b32 v254, s2, 6
	s_add_i32 s2, s33, 0x13410
	s_cmp_eq_u32 s49, 0
	s_cselect_b64 s[52:53], -1, 0
	s_cmp_lg_u32 s49, 0
	v_writelane_b32 v254, s2, 7
	s_cselect_b64 s[2:3], -1, 0
	s_cmp_gt_u32 s49, 1
	v_writelane_b32 v254, s2, 8
	s_cselect_b64 s[92:93], -1, 0
	s_cmp_lg_u32 s49, 1
	v_writelane_b32 v254, s3, 9
	s_cselect_b64 s[2:3], -1, 0
	s_cmp_eq_u32 s49, 3
	s_cselect_b64 s[76:77], -1, 0
	s_cmp_lg_u32 s49, 3
	s_cselect_b64 s[62:63], -1, 0
	s_cmp_lt_u32 s49, 2
	v_writelane_b32 v254, s2, 10
	s_cselect_b64 s[80:81], -1, 0
	s_cmp_lg_u32 s49, 2
	v_writelane_b32 v254, s3, 11
	s_cselect_b64 s[2:3], -1, 0
	v_writelane_b32 v254, s2, 12
	v_lshrrev_b32_e32 v2, 20, v0
	v_lshrrev_b32_e32 v0, 10, v0
	v_writelane_b32 v254, s3, 13
	s_add_i32 s2, s65, 0x3f8
	v_writelane_b32 v254, s2, 14
	s_add_i32 s2, s65, 0x238
	v_writelane_b32 v254, s2, 15
	s_add_i32 s2, s65, 0xffffff3c
	v_writelane_b32 v254, s2, 16
	s_add_i32 s2, s65, 0x78
	v_writelane_b32 v254, s2, 17
	s_lshl_b32 s2, s65, 12
	s_add_u32 s3, s0, 0xdac8600
	v_writelane_b32 v254, s3, 18
	s_addc_u32 s3, s1, 0
	s_add_u32 s4, s0, 0xdac8800
	v_writelane_b32 v254, s3, 19
	s_addc_u32 s5, s1, 0
	v_writelane_b32 v254, s4, 20
	v_or_b32_e32 v0, v0, v2
	s_mov_b32 s24, s26
	v_writelane_b32 v254, s5, 21
	s_add_u32 s4, s0, 0xdac8a00
	s_addc_u32 s5, s1, 0
	v_writelane_b32 v254, s4, 22
	v_mov_b32_e32 v161, 0
	v_mov_b32_e32 v252, 0x358637bd
	v_writelane_b32 v254, s5, 23
	s_add_u32 s4, s0, 0xdac8b00
	s_addc_u32 s5, s1, 0
	v_writelane_b32 v254, s4, 24
	v_mov_b32_e32 v163, 0x33ac000
	v_mov_b32_e32 v230, 0x33b4000
	v_writelane_b32 v254, s5, 25
	s_add_u32 s4, s0, 0xdac8c00
	s_addc_u32 s5, s1, 0
	v_writelane_b32 v254, s4, 26
	v_mov_b32_e32 v231, 0x3c0881c4
	v_mov_b32_e32 v247, 0xbab64f3b
	v_writelane_b32 v254, s5, 27
	s_add_u32 s4, s0, 0xdac8d00
	s_addc_u32 s5, s1, 0
	v_writelane_b32 v254, s4, 28
	v_mov_b32_e32 v162, 0x7f800000
	v_not_b32_e32 v250, 63
	v_writelane_b32 v254, s5, 29
	s_add_u32 s4, s0, 0xdac8e00
	s_addc_u32 s5, s1, 0
	v_writelane_b32 v254, s4, 30
	v_not_b32_e32 v246, 31
	v_mov_b32_e32 v251, 0x7fc00000
	v_writelane_b32 v254, s5, 31
	s_add_u32 s4, s0, 0xdac8f00
	s_addc_u32 s5, s1, 0
	v_writelane_b32 v254, s4, 32
	s_movk_i32 s39, 0x4000
	s_movk_i32 s42, 0xc00
	v_writelane_b32 v254, s5, 33
	s_add_u32 s4, s0, 0xdac9000
	s_addc_u32 s5, s1, 0
	v_writelane_b32 v254, s4, 34
	s_mov_b32 s84, 0x800000
	s_movk_i32 s85, 0x60
	v_writelane_b32 v254, s5, 35
	s_add_u32 s4, s0, 0xdac9100
	s_addc_u32 s5, s1, 0
	v_writelane_b32 v254, s4, 36
	s_mov_b32 s56, 0x3fb8aa3b
	s_movk_i32 s90, 0x42
	v_writelane_b32 v254, s5, 37
	s_add_u32 s4, s0, 0xdac9200
	s_addc_u32 s5, s1, 0
	v_writelane_b32 v254, s4, 38
	s_mov_b32 s91, 0x3f317217
	s_movk_i32 s68, 0x1020
	v_writelane_b32 v254, s5, 39
	s_add_u32 s4, s0, 0xdac9300
	s_addc_u32 s5, s1, 0
	v_writelane_b32 v254, s4, 40
	s_movk_i32 s61, 0x204
	s_mov_b32 s69, 0
	v_writelane_b32 v254, s5, 41
	s_add_u32 s4, s0, 0xdac9400
	s_addc_u32 s5, s1, 0
	v_writelane_b32 v254, s4, 42
	s_mov_b64 s[70:71], 0x7668680
	s_mov_b64 s[74:75], 0x75b8700
	v_writelane_b32 v254, s5, 43
	s_add_u32 s4, s0, 0xdac9500
	s_addc_u32 s5, s1, 0
	v_writelane_b32 v254, s4, 44
	s_mov_b64 s[78:79], 0x7668700
	s_mov_b64 s[82:83], 0x75b8780
	v_writelane_b32 v254, s5, 45
	s_add_u32 s4, s0, 0xdac9600
	s_addc_u32 s5, s1, 0
	v_writelane_b32 v254, s4, 46
	s_mov_b64 s[86:87], 0x100
	s_mov_b64 s[88:89], 0x40080
	v_writelane_b32 v254, s5, 47
	s_add_u32 s4, s0, 0xdac9700
	s_addc_u32 s5, s1, 0
	v_writelane_b32 v254, s4, 48
	s_mov_b64 s[94:95], 0x40100
	s_mov_b64 s[40:41], 0x180
	v_writelane_b32 v254, s5, 49
	s_add_u32 s4, s0, 0xdac9800
	s_addc_u32 s5, s1, 0
	v_writelane_b32 v254, s4, 50
	s_nop 1
	v_writelane_b32 v254, s5, 51
	s_add_u32 s4, s0, 0xdac9900
	s_addc_u32 s5, s1, 0
	v_writelane_b32 v254, s4, 52
	s_nop 1
	v_writelane_b32 v254, s5, 53
	s_add_u32 s4, s0, 0xdacba00
	s_addc_u32 s5, s1, 0
	v_writelane_b32 v254, s4, 54
	s_add_u32 s0, s0, 0xdacbb00
	s_addc_u32 s1, s1, 0
	v_writelane_b32 v254, s5, 55
	v_writelane_b32 v254, s0, 56
	s_nop 1
	v_writelane_b32 v254, s1, 57
	s_movk_i32 s0, 0x3ff
	v_and_or_b32 v0, v0, s0, v1
	s_add_i32 s0, s2, 0xffe7e000
	v_writelane_b32 v254, s0, 58
	s_lshl_b32 s0, s65, 13
	s_add_i32 s0, s0, 0xffcfc000
	v_writelane_b32 v254, s0, 59
	s_add_i32 s0, s33, 0x4800
	v_writelane_b32 v254, s0, 60
	s_add_i32 s0, 0, 0x10000
	v_writelane_b32 v254, s0, 61
	s_add_i32 s0, 0, 0x14000
	v_writelane_b32 v254, s0, 62
	s_add_i32 s0, 0, 0x18000
	v_writelane_b32 v254, s0, 63
	s_add_i32 s0, 0, 0x1c000
	v_writelane_b32 v255, s0, 0
	v_cmp_eq_u32_e64 s[0:1], 0, v0
	s_nop 1
	v_writelane_b32 v255, s0, 1
	s_nop 1
	v_writelane_b32 v255, s1, 2
	v_writelane_b32 v255, s50, 3
	s_nop 1
	v_writelane_b32 v255, s51, 4
	v_writelane_b32 v255, s26, 5
	s_nop 1
	v_writelane_b32 v255, s27, 6
	s_mov_b32 s0, 0
	v_writelane_b32 v255, s0, 21
	s_branch .LBB0_23

.LBB0_79:
	s_lshl_b32 s3, s64, 1
	s_add_i32 s3, s3, s65
	v_mbcnt_lo_u32_b32 v0, -1, 0
	v_mbcnt_hi_u32_b32 v0, -1, v0
	s_mov_b32 s72, s65
	v_add_u32_e32 v0, s48, v0
	s_load_dwordx2 s[22:23], s[54:55], 0x98
	s_load_dwordx2 s[24:25], s[54:55], 0xa0
	s_load_dwordx2 s[28:29], s[54:55], 0xa8
	s_bfe_u32 s30, s3, 0x40006
	s_lshl_b32 s30, s30, 2
	v_and_b32_e32 v201, 63, v0
	v_lshlrev_b32_e32 v201, 2, v201
	v_mov_b32_e32 v202, s30
	s_waitcnt lgkmcnt(0)
	global_load_dword v198, v201, s[22:23]
	global_load_dword v199, v201, s[24:25]
	global_load_dword v200, v202, s[28:29]
	s_and_b32 s65, s3, 63
	s_lshr_b32 s0, s3, 6
	s_ashr_i32 s6, s3, 10
	v_and_b32_e32 v20, 1, v0
	v_sub_co_u32_e64 v1, s[8:9], s65, 1
	s_bfe_u32 s2, s0, 0x20002
	v_bfe_u32 v130, v0, 1, 7
	v_readfirstlane_b32 s0, v1
	s_lshl_b32 s1, s6, 13
	s_mov_b64 s[4:5], -1
	s_andn2_b64 vcc, exec, s[8:9]
	v_lshlrev_b32_e32 v160, 5, v20
	s_cbranch_vccz .LBB0_81
	s_lshl_b32 s4, s0, 7
	s_add_i32 s4, s4, s1
	v_or_b32_e32 v1, s4, v130
	v_mov_b64_e32 v[2:3], s[66:67]
	v_mad_i64_i32 v[2:3], s[4:5], v1, s7, v[2:3]
	s_lshl_b32 s4, s2, 7
	s_mov_b32 s5, s69
	v_lshl_add_u64 v[2:3], v[2:3], 0, s[4:5]
	v_lshlrev_b32_e32 v4, 6, v20
	v_mov_b32_e32 v5, v161
	v_lshl_add_u64 v[2:3], v[2:3], 0, v[4:5]
	global_load_dwordx4 v[78:81], v[2:3], off offset:2096
	global_load_dwordx4 v[82:85], v[2:3], off offset:2080
	global_load_dwordx4 v[86:89], v[2:3], off offset:2064
	global_load_dwordx4 v[90:93], v[2:3], off offset:2048
	global_load_dwordx4 v[94:97], v[2:3], off offset:2560
	global_load_dwordx4 v[98:101], v[2:3], off offset:2576
	global_load_dwordx4 v[102:105], v[2:3], off offset:2592
	global_load_dwordx4 v[106:109], v[2:3], off offset:2608
	s_lshl_b32 s68, s2, 6
	s_mov_b64 s[4:5], 0
	v_mov_b64_e32 v[16:17], s[68:69]
	v_mov_b64_e32 v[18:19], v[160:161]

.LBB0_83:
	v_and_b32_e32 v1, 63, v0
	v_lshlrev_b32_e32 v1, 2, v1
	s_lshl_b32 s2, s3, 2
	v_mov_b32_e32 v2, s2
	s_waitcnt lgkmcnt(0)
	v_lshrrev_b32_e32 v7, 1, v0
	v_and_b32_e32 v21, 31, v0
	v_bfe_u32 v8, v0, 5, 1
	v_lshlrev_b32_e32 v131, 2, v8
	s_waitcnt lgkmcnt(0)
	s_lshl_b32 s4, s65, 7
	s_movk_i32 s5, 0x60
	s_or_b32 s4, s1, s4
	v_and_or_b32 v132, v7, s5, v21
	v_or_b32_e32 v126, s4, v132
	v_readlane_b32 s4, v254, 4
	v_mov_b64_e32 v[2:3], s[66:67]
	s_lshl_b32 s68, s3, 7
	v_or_b32_e32 v134, s4, v131
	s_movk_i32 s4, 0xc00
	v_mad_i64_i32 v[2:3], s[4:5], v126, s4, v[2:3]
	v_lshlrev_b32_e32 v160, 4, v8
	v_lshl_add_u64 v[2:3], v[2:3], 0, s[68:69]
	v_lshl_add_u64 v[2:3], v[2:3], 0, v[160:161]
	global_load_dwordx4 v[110:113], v[2:3], off
	global_load_dwordx4 v[114:117], v[2:3], off offset:32
	global_load_dwordx4 v[118:121], v[2:3], off offset:64
	global_load_dwordx4 v[122:125], v[2:3], off offset:96
	v_xor_b32_e32 v133, 0x80, v1
	v_lshlrev_b64 v[16:17], 1, v[16:17]
	v_mul_u32_u24_e32 v23, 0x84, v21
	v_lshl_add_u64 v[16:17], s[66:67], 0, v[16:17]
	v_mov_b32_e32 v0, v161
	v_lshlrev_b32_e32 v22, 3, v8
	v_lshl_add_u64 v[128:129], v[18:19], 1, v[16:17]
	v_lshlrev_b32_e32 v16, 1, v23
	v_readlane_b32 s4, v254, 60
	s_lshl_b32 s50, s6, 8
	v_mul_u32_u24_e32 v153, 0x2100, v20
	v_add3_u32 v154, v22, v16, s4
	v_mul_u32_u24_e32 v16, 0x90, v21
	v_add3_u32 v156, v16, v160, s33
	v_lshlrev_b32_e32 v157, 1, v18
	s_lshl_b32 s2, s3, 6
	s_mov_b32 s3, 0
	s_addk_i32 s50, 0x3f00
	v_ashrrev_i32_e32 v127, 31, v126
	s_movk_i32 s68, 0xc00
	v_or_b32_e32 v135, 1, v134
	v_or_b32_e32 v136, 2, v134
	v_or_b32_e32 v137, 3, v134
	v_or_b32_e32 v139, 8, v134
	v_or_b32_e32 v140, 9, v134
	v_or_b32_e32 v142, 10, v134
	v_or_b32_e32 v143, 11, v134
	v_or_b32_e32 v144, 16, v134
	v_or_b32_e32 v145, 17, v134
	v_or_b32_e32 v146, 18, v134
	v_or_b32_e32 v147, 19, v134
	v_or_b32_e32 v148, 24, v134
	v_or_b32_e32 v149, 25, v134
	v_or_b32_e32 v150, 26, v134
	v_or_b32_e32 v151, 27, v134
	v_mul_u32_u24_e32 v152, 0x90, v130
	s_waitcnt vmcnt(0)
	v_mov_b32_e32 v4, v198
	v_mov_b32_e32 v5, v199
	v_mov_b32_e32 v6, v200
	v_and_b32_e32 v1, 0x7fffffff, v4
	v_and_b32_e32 v2, 0x7fffffff, v5
	s_nop 0
	v_mov_b32_dpp v1, v1 quad_perm:[1,0,3,2] row_mask:0xf bank_mask:0xf bound_ctrl:1
	v_max_f32_e64 v3, |v4|, |v4|
	v_mov_b32_dpp v2, v2 quad_perm:[1,0,3,2] row_mask:0xf bank_mask:0xf bound_ctrl:1
	v_max_f32_e32 v1, v1, v1
	v_max_f32_e64 v4, |v5|, |v5|
	v_max_f32_e32 v2, v2, v2
	v_max_f32_e32 v1, v3, v1
	v_max_f32_e32 v2, v4, v2
	v_mul_f32_e32 v138, 0x3fb8aa3b, v6
	v_mov_b32_dpp v3, v1 quad_perm:[2,3,0,1] row_mask:0xf bank_mask:0xf bound_ctrl:1
	v_mov_b32_dpp v4, v2 quad_perm:[2,3,0,1] row_mask:0xf bank_mask:0xf bound_ctrl:1
	v_max_f32_e32 v3, v3, v3
	v_max_f32_e32 v4, v4, v4
	v_max_f32_e32 v1, v1, v3
	v_max_f32_e32 v2, v2, v4
	s_nop 0
	v_mov_b32_dpp v3, v1 row_half_mirror row_mask:0xf bank_mask:0xf bound_ctrl:1
	v_mov_b32_dpp v4, v2 row_half_mirror row_mask:0xf bank_mask:0xf bound_ctrl:1
	v_max_f32_e32 v3, v3, v3
	v_max_f32_e32 v4, v4, v4
	v_max_f32_e32 v1, v1, v3
	v_max_f32_e32 v2, v2, v4
	s_nop 0
	v_mov_b32_dpp v3, v1 row_mirror row_mask:0xf bank_mask:0xf bound_ctrl:1
	v_mov_b32_dpp v4, v2 row_mirror row_mask:0xf bank_mask:0xf bound_ctrl:1
	v_max_f32_e32 v3, v3, v3
	v_max_f32_e32 v4, v4, v4
	v_max_f32_e32 v1, v1, v3
	v_max_f32_e32 v2, v2, v4
	ds_swizzle_b32 v3, v1 offset:swizzle(SWAP,16)
	ds_swizzle_b32 v4, v2 offset:swizzle(SWAP,16)
	s_waitcnt lgkmcnt(1)
	v_max_f32_e32 v3, v3, v3
	s_waitcnt lgkmcnt(0)
	v_max_f32_e32 v4, v4, v4
	v_max_f32_e32 v1, v1, v3
	v_max_f32_e32 v2, v2, v4
	ds_bpermute_b32 v3, v133, v1
	ds_bpermute_b32 v4, v133, v2
	s_waitcnt lgkmcnt(1)
	v_max_f32_e32 v3, v3, v3
	s_waitcnt lgkmcnt(0)
	v_max_f32_e32 v4, v4, v4
	v_max_f32_e32 v1, v1, v3
	v_max_f32_e32 v2, v2, v4
	v_mul_f32_e32 v1, 0x4138aa3b, v1
	v_mul_f32_e32 v1, v1, v2
	v_max_f32_e32 v141, v1, v138
	v_xor_b32_e32 v32, 0x80000000, v141
	s_nop 0
	v_mov_b32_e32 v14, v0
	v_mov_b32_e32 v15, v0
	v_mov_b32_e32 v1, v0
	v_mov_b32_e32 v2, v0
	v_mov_b32_e32 v3, v0
	v_mov_b32_e32 v4, v0
	v_mov_b32_e32 v5, v0
	v_mov_b32_e32 v6, v0
	v_mov_b32_e32 v7, v0
	v_mov_b32_e32 v8, v0
	v_mov_b32_e32 v9, v0
	v_mov_b32_e32 v10, v0
	v_mov_b32_e32 v11, v0
	v_mov_b32_e32 v12, v0
	v_mov_b32_e32 v13, v0
	v_mov_b64_e32 v[30:31], v[14:15]
	v_mov_b32_e32 v33, v32
	v_mov_b32_e32 v34, v32
	v_mov_b32_e32 v35, v32
	v_mov_b32_e32 v36, v32
	v_mov_b32_e32 v37, v32
	v_mov_b32_e32 v38, v32
	v_mov_b32_e32 v39, v32
	v_mov_b32_e32 v40, v32
	v_mov_b32_e32 v41, v32
	v_mov_b32_e32 v42, v32
	v_mov_b32_e32 v43, v32
	v_mov_b32_e32 v44, v32
	v_mov_b32_e32 v45, v32
	v_mov_b32_e32 v46, v32
	v_mov_b32_e32 v47, v32
	v_mov_b64_e32 v[28:29], v[12:13]
	v_mov_b64_e32 v[26:27], v[10:11]
	v_mov_b64_e32 v[24:25], v[8:9]
	v_mov_b64_e32 v[22:23], v[6:7]
	v_mov_b64_e32 v[20:21], v[4:5]
	v_mov_b64_e32 v[18:19], v[2:3]
	v_mov_b64_e32 v[16:17], v[0:1]
	v_mov_b32_e32 v155, v0
	s_branch .LBB0_86

.LBB0_91:
	s_and_b64 vcc, exec, s[4:5]
	s_cbranch_vccnz .LBB0_85
	s_cmp_eq_u32 s3, 0
	s_cselect_b64 s[4:5], -1, 0
	s_mov_b64 s[84:85], s[80:81]
	s_mov_b64 s[80:81], s[76:77]
	s_mov_b64 s[76:77], s[92:93]
	s_cmp_eq_u32 s3, 2
	s_cselect_b64 s[92:93], -1, 0
	s_lshl_b32 s42, s42, 1
	s_mov_b64 s[56:57], s[96:97]
	s_mov_b32 s51, 0
	s_or_b64 s[96:97], s[4:5], s[92:93]
	v_add_u32_e32 v158, s42, v154
	v_add_u32_e32 v159, s42, v156
	s_and_b64 vcc, exec, s[96:97]
	s_cbranch_vccz .LBB0_95
	s_and_b64 vcc, exec, s[4:5]
	s_cbranch_vccz .Lattn_mask_le
	v_cmp_ge_i32_e64 s[6:7], v134, v132
	v_cmp_ge_i32_e64 s[8:9], v135, v132
	v_cmp_ge_i32_e64 s[10:11], v136, v132
	v_cmp_ge_i32_e64 s[12:13], v137, v132
	v_cmp_ge_i32_e64 s[14:15], v139, v132
	v_cmp_ge_i32_e64 s[16:17], v140, v132
	v_cmp_ge_i32_e64 s[18:19], v142, v132
	v_cmp_ge_i32_e64 s[20:21], v143, v132
	v_cmp_ge_i32_e64 s[22:23], v144, v132
	v_cmp_ge_i32_e64 s[24:25], v145, v132
	v_cmp_ge_i32_e64 s[26:27], v146, v132
	v_cmp_ge_i32_e64 s[28:29], v147, v132
	v_cmp_ge_i32_e64 s[30:31], v148, v132
	v_cmp_ge_i32_e64 s[34:35], v149, v132
	v_cmp_ge_i32_e64 s[36:37], v150, v132
	v_cmp_ge_i32_e64 s[38:39], v151, v132
	s_branch .LBB0_95
.Lattn_mask_le:
	v_cmp_le_i32_e64 s[6:7], v134, v132
	v_cmp_le_i32_e64 s[8:9], v135, v132
	v_cmp_le_i32_e64 s[10:11], v136, v132
	v_cmp_le_i32_e64 s[12:13], v137, v132
	v_cmp_le_i32_e64 s[14:15], v139, v132
	v_cmp_le_i32_e64 s[16:17], v140, v132
	v_cmp_le_i32_e64 s[18:19], v142, v132
	v_cmp_le_i32_e64 s[20:21], v143, v132
	v_cmp_le_i32_e64 s[22:23], v144, v132
	v_cmp_le_i32_e64 s[24:25], v145, v132
	v_cmp_le_i32_e64 s[26:27], v146, v132
	v_cmp_le_i32_e64 s[28:29], v147, v132
	v_cmp_le_i32_e64 s[30:31], v148, v132
	v_cmp_le_i32_e64 s[34:35], v149, v132
	v_cmp_le_i32_e64 s[36:37], v150, v132
	v_cmp_le_i32_e64 s[38:39], v151, v132
	s_branch .LBB0_95

.LBB0_95:
	s_cmp_lt_u32 s51, s49
	s_cselect_b64 s[42:43], -1, 0
	s_and_b64 s[42:43], s[4:5], s[42:43]
	s_cmp_gt_u32 s51, s49
	s_cselect_b64 vcc, -1, 0
	s_and_b64 vcc, s[92:93], vcc
	s_or_b64 s[42:43], s[42:43], vcc
	s_and_b64 vcc, exec, s[42:43]
	s_cbranch_vccnz .LBB0_94
	ds_read_b128 v[48:51], v159
	ds_read_b128 v[204:207], v159 offset:32
	ds_read_b128 v[208:211], v159 offset:64
	ds_read_b128 v[212:215], v159 offset:96
	s_cmp_eq_u32 s49, s51
	s_cselect_b64 vcc, -1, 0
	s_and_b64 vcc, s[96:97], vcc
	s_mov_b64 s[42:43], -1
	s_and_b64 vcc, exec, vcc
	s_waitcnt lgkmcnt(3)
	v_mfma_f32_32x32x16_bf16 v[62:77], v[48:51], v[110:113], v[32:47]
	s_waitcnt lgkmcnt(2)
	v_mfma_f32_32x32x16_bf16 v[62:77], v[204:207], v[114:117], v[62:77]
	s_waitcnt lgkmcnt(1)
	v_mfma_f32_32x32x16_bf16 v[62:77], v[208:211], v[118:121], v[62:77]
	s_waitcnt lgkmcnt(0)
	v_mfma_f32_32x32x16_bf16 v[62:77], v[212:215], v[122:125], v[62:77]
	s_nop 11
	v_exp_f32_e32 v62, v62
	v_exp_f32_e32 v63, v63
	v_exp_f32_e32 v56, v64
	v_exp_f32_e32 v57, v65
	v_exp_f32_e32 v58, v66
	v_exp_f32_e32 v59, v67
	v_exp_f32_e32 v60, v68
	v_exp_f32_e32 v61, v69
	v_exp_f32_e32 v48, v70
	v_exp_f32_e32 v49, v71
	v_exp_f32_e32 v50, v72
	v_exp_f32_e32 v51, v73
	v_exp_f32_e32 v52, v74
	v_exp_f32_e32 v53, v75
	v_exp_f32_e32 v54, v76
	v_exp_f32_e32 v55, v77
	s_cbranch_vccnz .LBB0_98
	s_mov_b64 s[42:43], 0

.Lres_spin_p9:
	global_load_dword v236, v238, s[4:5] sc1
	s_add_i32 s98, s98, 1
	s_waitcnt vmcnt(0)
	v_readfirstlane_b32 s38, v236
	s_cmp_ge_u32 s38, 11
	s_cbranch_scc1 .Lres_go_p9
	s_cmp_gt_u32 s98, 0x40000
	s_cbranch_scc1 .Lres_go_p9
	s_sleep 2
	s_branch .Lres_spin_p9

.Lres_spin_p6:
	global_load_dword v236, v238, s[98:99] sc1
	s_add_i32 s67, s67, 1
	s_waitcnt vmcnt(0)
	v_readfirstlane_b32 s36, v236
	s_cmp_ge_u32 s36, 4
	s_cbranch_scc1 .Lres_go_p6
	s_cmp_gt_u32 s67, 0x40000
	s_cbranch_scc1 .Lres_go_p6
	s_sleep 2
	s_branch .Lres_spin_p6

.LBB0_1160:
	s_cmp_ge_i32 s66, s26
	s_cbranch_scc0 .LBB0_1216
	s_waitcnt vmcnt(0)
	v_readlane_b32 s0, v254, 0
	v_readlane_b32 s1, v254, 1
	s_andn2_b64 vcc, exec, s[0:1]
	s_waitcnt vmcnt(0)
	s_barrier
	s_cbranch_vccnz .LBB0_1215
	v_mbcnt_lo_u32_b32 v0, -1, 0
	v_mbcnt_hi_u32_b32 v0, -1, v0
	v_cmp_eq_u32_e32 vcc, 0, v0
	s_and_saveexec_b64 s[4:5], vcc
	s_cbranch_execz .LBB0_1214
	v_readlane_b32 s6, v254, 18
	v_readlane_b32 s7, v254, 19
	s_getreg_b32 s8, hwreg(HW_REG_XCC_ID, 0, 4)
	s_and_b32 s8, s8, 15
	v_readlane_b32 s9, v255, 21
	v_readlane_b32 s10, v255, 22
	v_readlane_b32 s11, v255, 23
	v_mov_b32_e32 v1, 0
	v_mov_b32_e32 v2, 1
	s_add_u32 s18, s6, 0x3400
	s_addc_u32 s19, s7, 0
	s_cmp_lg_u32 s9, 0
	s_cbranch_scc1 .Lgb_have_counts
	v_readlane_b32 s12, v255, 7
	s_add_u32 s16, s6, 0x400
	s_addc_u32 s17, s7, 0
	s_mov_b32 s13, 0
.Lgb_cnt_spin:
	global_load_dword v3, v1, s[16:17] sc1
	global_load_dword v4, v1, s[16:17] offset:256 sc1
	global_load_dword v5, v1, s[16:17] offset:512 sc1
	global_load_dword v6, v1, s[16:17] offset:768 sc1
	global_load_dword v7, v1, s[16:17] offset:1024 sc1
	global_load_dword v8, v1, s[16:17] offset:1280 sc1
	global_load_dword v9, v1, s[16:17] offset:1536 sc1
	global_load_dword v10, v1, s[16:17] offset:1792 sc1
	global_load_dword v11, v1, s[16:17] offset:2048 sc1
	global_load_dword v12, v1, s[16:17] offset:2304 sc1
	global_load_dword v13, v1, s[16:17] offset:2560 sc1
	global_load_dword v14, v1, s[16:17] offset:2816 sc1
	global_load_dword v15, v1, s[16:17] offset:3072 sc1
	global_load_dword v16, v1, s[16:17] offset:3328 sc1
	global_load_dword v17, v1, s[16:17] offset:3584 sc1
	global_load_dword v18, v1, s[16:17] offset:3840 sc1
	s_add_i32 s13, s13, 1
	s_waitcnt vmcnt(0)
	s_mov_b32 s14, 0
	s_mov_b32 s15, 0
	s_mov_b32 s20, 0
	v_readfirstlane_b32 s21, v3
	s_add_i32 s14, s14, s21
	s_cmp_lg_u32 s21, 0
	s_addc_u32 s15, s15, 0
	s_cmp_eq_u32 s8, 0
	s_cselect_b32 s20, s21, s20
	v_readfirstlane_b32 s21, v4
	s_add_i32 s14, s14, s21
	s_cmp_lg_u32 s21, 0
	s_addc_u32 s15, s15, 0
	s_cmp_eq_u32 s8, 1
	s_cselect_b32 s20, s21, s20
	v_readfirstlane_b32 s21, v5
	s_add_i32 s14, s14, s21
	s_cmp_lg_u32 s21, 0
	s_addc_u32 s15, s15, 0
	s_cmp_eq_u32 s8, 2
	s_cselect_b32 s20, s21, s20
	v_readfirstlane_b32 s21, v6
	s_add_i32 s14, s14, s21
	s_cmp_lg_u32 s21, 0
	s_addc_u32 s15, s15, 0
	s_cmp_eq_u32 s8, 3
	s_cselect_b32 s20, s21, s20
	v_readfirstlane_b32 s21, v7
	s_add_i32 s14, s14, s21
	s_cmp_lg_u32 s21, 0
	s_addc_u32 s15, s15, 0
	s_cmp_eq_u32 s8, 4
	s_cselect_b32 s20, s21, s20
	v_readfirstlane_b32 s21, v8
	s_add_i32 s14, s14, s21
	s_cmp_lg_u32 s21, 0
	s_addc_u32 s15, s15, 0
	s_cmp_eq_u32 s8, 5
	s_cselect_b32 s20, s21, s20
	v_readfirstlane_b32 s21, v9
	s_add_i32 s14, s14, s21
	s_cmp_lg_u32 s21, 0
	s_addc_u32 s15, s15, 0
	s_cmp_eq_u32 s8, 6
	s_cselect_b32 s20, s21, s20
	v_readfirstlane_b32 s21, v10
	s_add_i32 s14, s14, s21
	s_cmp_lg_u32 s21, 0
	s_addc_u32 s15, s15, 0
	s_cmp_eq_u32 s8, 7
	s_cselect_b32 s20, s21, s20
	v_readfirstlane_b32 s21, v11
	s_add_i32 s14, s14, s21
	s_cmp_lg_u32 s21, 0
	s_addc_u32 s15, s15, 0
	s_cmp_eq_u32 s8, 8
	s_cselect_b32 s20, s21, s20
	v_readfirstlane_b32 s21, v12
	s_add_i32 s14, s14, s21
	s_cmp_lg_u32 s21, 0
	s_addc_u32 s15, s15, 0
	s_cmp_eq_u32 s8, 9
	s_cselect_b32 s20, s21, s20
	v_readfirstlane_b32 s21, v13
	s_add_i32 s14, s14, s21
	s_cmp_lg_u32 s21, 0
	s_addc_u32 s15, s15, 0
	s_cmp_eq_u32 s8, 10
	s_cselect_b32 s20, s21, s20
	v_readfirstlane_b32 s21, v14
	s_add_i32 s14, s14, s21
	s_cmp_lg_u32 s21, 0
	s_addc_u32 s15, s15, 0
	s_cmp_eq_u32 s8, 11
	s_cselect_b32 s20, s21, s20
	v_readfirstlane_b32 s21, v15
	s_add_i32 s14, s14, s21
	s_cmp_lg_u32 s21, 0
	s_addc_u32 s15, s15, 0
	s_cmp_eq_u32 s8, 12
	s_cselect_b32 s20, s21, s20
	v_readfirstlane_b32 s21, v16
	s_add_i32 s14, s14, s21
	s_cmp_lg_u32 s21, 0
	s_addc_u32 s15, s15, 0
	s_cmp_eq_u32 s8, 13
	s_cselect_b32 s20, s21, s20
	v_readfirstlane_b32 s21, v17
	s_add_i32 s14, s14, s21
	s_cmp_lg_u32 s21, 0
	s_addc_u32 s15, s15, 0
	s_cmp_eq_u32 s8, 14
	s_cselect_b32 s20, s21, s20
	v_readfirstlane_b32 s21, v18
	s_add_i32 s14, s14, s21
	s_cmp_lg_u32 s21, 0
	s_addc_u32 s15, s15, 0
	s_cmp_eq_u32 s8, 15
	s_cselect_b32 s20, s21, s20
	s_cmp_eq_u32 s14, s12
	s_cbranch_scc1 .Lgb_cnt_done
	s_cmp_gt_u32 s13, 0x40000
	s_cbranch_scc1 .Lgb_cnt_done
	s_sleep 1
	s_branch .Lgb_cnt_spin
.Lgb_cnt_done:
	s_max_u32 s10, s20, 1
	s_max_u32 s11, s15, 1
	v_writelane_b32 v255, s10, 22
	v_writelane_b32 v255, s11, 23
.Lgb_have_counts:
	s_add_i32 s12, s9, 1
	s_mul_i32 s13, s10, s12
	s_mul_i32 s14, s11, s12
	s_lshl_b32 s15, s8, 8
	s_add_u32 s16, s6, s15
	s_addc_u32 s17, s7, 0
	s_add_u32 s16, s16, 0x1400
	s_addc_u32 s17, s17, 0
	global_atomic_add v3, v1, v2, s[16:17] sc0
	s_waitcnt vmcnt(0)
	v_readfirstlane_b32 s15, v3
	s_add_i32 s15, s15, 1
	s_cmp_lg_u32 s15, s13
	s_cbranch_scc1 .Lgb_wait
	buffer_wbl2 sc1
	s_waitcnt vmcnt(0)
	global_atomic_add v1, v2, s[18:19]
.Lgb_wait:
	s_mov_b32 s20, 0
.Lgb_spin:
	global_load_dword v4, v1, s[18:19] sc1
	s_add_i32 s20, s20, 1
	s_waitcnt vmcnt(0)
	v_readfirstlane_b32 s21, v4
	s_cmp_ge_u32 s21, s14
	s_cbranch_scc1 .Lgb_done
	s_cmp_gt_u32 s20, 0x40000
	s_cbranch_scc1 .Lgb_done
	s_sleep 1
	s_branch .Lgb_spin
.Lgb_done:
	buffer_inv sc1
	v_writelane_b32 v255, s12, 21
